# batch barrier: same-XCC case issues the L1 invalidate right after arrival (overlaps the wait), poll without sleep
# speedup vs baseline: 1.0221x; 1.0055x over previous
; __device__ __forceinline__ unsigned xb_ld(unsigned* p)              { return __hip_atomic_load(p, __ATOMIC_RELAXED, __HIP_MEMORY_SCOPE_AGENT); }
; __device__ __forceinline__ unsigned xb_add(unsigned* p, unsigned v) { return __hip_atomic_fetch_add(p, v, __ATOMIC_RELAXED, __HIP_MEMORY_SCOPE_AGENT); }
; #define XB_SPIN(cond, bar) do { unsigned _sp = 0; while (cond) { __builtin_amdgcn_s_sleep(1); \
;     if ((++_sp & 255u) == 0u) { if (xb_ld(&(bar)[XB_TMO])) break; if (_sp > XB_SPIN_CAP) { atomicAdd(&(bar)[XB_TMO], 1u); break; } } } } while (0)
; __device__ __forceinline__ void xcd_barrier(const XcdBarrier& b) {
;     asm volatile("s_waitcnt vmcnt(0)" ::: "memory");
;     __syncthreads();
;     if (threadIdx.x == 0) {
;         unsigned* bar = b.bar;
;         __builtin_amdgcn_s_waitcnt(0);
;         unsigned nloc = b.st[0], nx = b.st[1];
;         if (nloc == 0u) { xcd_barrier_complete(bar, b.x, nloc, nx); b.st[0] = nloc; b.st[1] = nx; }
;         const unsigned old = xb_add(&bar[XB_XSUB(b.x)], 1u);
;         const unsigned gen = old / nloc;
;         if (old + 1u == (gen + 1u) * nloc) {
;             __builtin_amdgcn_fence(__ATOMIC_RELEASE, "agent");
;             asm volatile("s_waitcnt vmcnt(0)" ::: "memory");
;             const unsigned og = xb_add(&bar[XB_TOP], 1u);
;             const unsigned tg = og / nx;
;             if (og + 1u == (tg + 1u) * nx) xb_add(&bar[XB_TOPGEN], 1u);
;             else XB_SPIN(xb_ld(&bar[XB_TOPGEN]) == tg, bar);
;             __builtin_amdgcn_fence(__ATOMIC_ACQUIRE, "agent");
;             xb_add(&bar[XB_XGEN(b.x)], 1u);
;             asm volatile("s_waitcnt vmcnt(0)" ::: "memory");
;         } else {
;             XB_SPIN(xb_ld(&bar[XB_XGEN(b.x)]) == gen, bar);
;             __builtin_amdgcn_fence(__ATOMIC_ACQUIRE, "agent");
;             asm volatile("s_waitcnt vmcnt(0)" ::: "memory");
;         }
;     }
;     __syncthreads();
; }
.Lbbsb_fast:
	global_atomic_add v0, v2, s[8:9]
	s_cmp_eq_u32 s100, 1
	s_cbranch_scc0 .Lbbsb_noearly
	buffer_inv sc1
.Lbbsb_noearly:
	s_mov_b32 s10, 0
.Lbbsb_spin:
	global_load_dword v1, v0, s[8:9] sc1
	s_waitcnt vmcnt(0)
	v_readfirstlane_b32 s11, v1
	s_cmp_ge_u32 s11, s6
	s_cbranch_scc1 .Lbbsb_done
	s_add_i32 s10, s10, 1
	s_cmp_lt_u32 s10, 0x2000
	s_cbranch_scc1 .Lbbsb_spin
.Lbbsb_done:
	s_cmp_eq_u32 s100, 1
	s_cbranch_scc1 .Lbbsb_join
	buffer_inv sc1
	s_waitcnt vmcnt(0)
